# merge odd-epilogue: first-half gate/merged loads pre-issued in the last K iteration before the closing barrier (on top of v54)
# baseline (speedup 1.0000x reference)
; #define PG8_STAGE(bufoff, gbase, voff) do { _Pragma("unroll") for (int _i = 0; _i < 2; ++_i) \
;         __builtin_amdgcn_global_load_lds((const unsigned*)((const char*)(gbase) + (voff)[_i]), (LAS unsigned*)(lds + (bufoff) + ldsw + _i * 8192), 16, 0, 0); } while (0)
; #define PG8_LDA(dst, b, h) do { _Pragma("unroll") for (int m = 0; m < 4; ++m) _Pragma("unroll") for (int k = 0; k < 2; ++k) dst[m][k] = *(const LAS bf16x8*)(lds + PG8_SA(b, h) + aoff + m * 2048 + k * 1024); } while (0)
; #define PG8_LDB(dst, b, h) do { _Pragma("unroll") for (int n = 0; n < 2; ++n) _Pragma("unroll") for (int k = 0; k < 2; ++k) dst[n][k] = *(const LAS bf16x8*)(lds + PG8_SB(b, h) + boff + n * 2048 + k * 1024); } while (0)
; #define PG8_MMA(ai, bj, At, Bt) do { __builtin_amdgcn_s_setprio(1); _Pragma("unroll") for (int m = 0; m < 4; ++m) _Pragma("unroll") for (int n = 0; n < 2; ++n) _Pragma("unroll") for (int k = 0; k < 2; ++k) \
;         acc[ai][bj][m][n] = __builtin_amdgcn_mfma_f32_16x16x32_bf16(Bt[n][k], At[m][k], acc[ai][bj][m][n], 0, 0, 0); __builtin_amdgcn_s_setprio(0); } while (0)
; #define PG8_WAIT_V(n) asm volatile("s_waitcnt vmcnt(" #n ")" ::: "memory")
; #define PG8_WAIT_L(n) asm volatile("s_waitcnt lgkmcnt(" #n ")" ::: "memory")
; #define PG8_BAR __builtin_amdgcn_s_barrier()
; #define PG8_SCHED __builtin_amdgcn_sched_barrier(0)
; template <class Epi, class Sched>
; __device__ __forceinline__ void gemm_phase(LAS unsigned char* lds, const int lda, const int ldb, const Sched& S, const Epi& E) {
;     ...
;             PG8_LDB(B0, 0, 0); PG8_LDB(B1, 0, 1); PG8_SCHED; PG8_LDA(At, 0, 0); PG8_STAGE(PG8_SA(1, 1), a1 + hstepA, voffA);
;             PG8_WAIT_V(8); PG8_WAIT_L(0); PG8_BAR; PG8_MMA(0, 0, At, B0); PG8_MMA(0, 1, At, B1); PG8_BAR; PG8_SCHED;
;             PG8_LDA(At, 0, 1); PG8_STAGE(PG8_SB(0, 0), b2, voffB); PG8_STAGE(PG8_SB(0, 1), b2 + hstepB, voffB); PG8_STAGE(PG8_SA(0, 0), a2, voffA);
;             PG8_WAIT_V(8); PG8_WAIT_L(0); PG8_BAR; PG8_MMA(1, 0, At, B0); PG8_MMA(1, 1, At, B1); PG8_BAR; PG8_SCHED;
.LBB0_662:
	s_add_i32 s61, s44, 2
	s_add_u32 s36, s22, 0x100
	s_addc_u32 s37, s23, 0
	s_add_i32 s62, 0, 0x10000
	s_cmp_eq_u32 s24, s44
	s_cselect_b32 s47, s19, s37
	s_cselect_b32 s46, s18, s36
	s_cselect_b32 s45, s21, s60
	s_cselect_b32 s44, s20, s25
	s_add_i32 s63, 0, 0x14000
	v_add_u32_e32 v142, s62, v241
	v_add_u32_e32 v158, s63, v241
	ds_read_b128 v[130:133], v142
	ds_read_b128 v[134:137], v142 offset:1024
	ds_read_b128 v[138:141], v142 offset:2048
	ds_read_b128 v[142:145], v142 offset:3072
	ds_read_b128 v[146:149], v158
	ds_read_b128 v[150:153], v158 offset:1024
	ds_read_b128 v[154:157], v158 offset:2048
	ds_read_b128 v[158:161], v158 offset:3072
	v_lshl_add_u64 v[216:217], s[22:23], 0, v[212:213]
	s_add_i32 m0, s27, 0xc000
	ds_read_b128 v[162:165], v244
	ds_read_b128 v[166:169], v244 offset:1024
	ds_read_b128 v[170:173], v244 offset:2048
	ds_read_b128 v[174:177], v244 offset:3072
	ds_read_b128 v[178:181], v244 offset:4096
	ds_read_b128 v[182:185], v244 offset:5120
	ds_read_b128 v[186:189], v244 offset:6144
	ds_read_b128 v[190:193], v244 offset:7168
	global_load_lds_dwordx4 v[216:217], off
	v_lshl_add_u64 v[216:217], s[22:23], 0, v[214:215]
	s_add_i32 m0, s27, 0xe000
	s_nop 0
	global_load_lds_dwordx4 v[216:217], off
	s_waitcnt vmcnt(8)
	s_waitcnt lgkmcnt(0)
	s_barrier
	s_setprio 1
	s_waitcnt lgkmcnt(0)
	v_mfma_f32_16x16x32_bf16 v[126:129], v[130:133], v[162:165], v[126:129]
	v_mfma_f32_16x16x32_bf16 v[122:125], v[138:141], v[162:165], v[122:125]
	v_mfma_f32_16x16x32_bf16 v[110:113], v[130:133], v[170:173], v[110:113]
	v_mfma_f32_16x16x32_bf16 v[106:109], v[138:141], v[170:173], v[106:109]
	v_mfma_f32_16x16x32_bf16 v[94:97], v[130:133], v[178:181], v[94:97]
	v_mfma_f32_16x16x32_bf16 v[90:93], v[138:141], v[178:181], v[90:93]
	v_mfma_f32_16x16x32_bf16 v[78:81], v[130:133], v[186:189], v[78:81]
	v_mfma_f32_16x16x32_bf16 v[74:77], v[138:141], v[186:189], v[74:77]
	v_mfma_f32_16x16x32_bf16 v[126:129], v[134:137], v[166:169], v[126:129]
	v_mfma_f32_16x16x32_bf16 v[122:125], v[142:145], v[166:169], v[122:125]
	v_mfma_f32_16x16x32_bf16 v[110:113], v[134:137], v[174:177], v[110:113]
	v_mfma_f32_16x16x32_bf16 v[106:109], v[142:145], v[174:177], v[106:109]
	v_mfma_f32_16x16x32_bf16 v[94:97], v[134:137], v[182:185], v[94:97]
	v_mfma_f32_16x16x32_bf16 v[90:93], v[142:145], v[182:185], v[90:93]
	v_mfma_f32_16x16x32_bf16 v[78:81], v[134:137], v[190:193], v[78:81]
	v_mfma_f32_16x16x32_bf16 v[74:77], v[142:145], v[190:193], v[74:77]
	s_setprio 0
	s_setprio 1
	v_mfma_f32_16x16x32_bf16 v[118:121], v[146:149], v[162:165], v[118:121]
	v_mfma_f32_16x16x32_bf16 v[114:117], v[154:157], v[162:165], v[114:117]
	v_mfma_f32_16x16x32_bf16 v[102:105], v[146:149], v[170:173], v[102:105]
	v_mfma_f32_16x16x32_bf16 v[98:101], v[154:157], v[170:173], v[98:101]
	v_mfma_f32_16x16x32_bf16 v[86:89], v[146:149], v[178:181], v[86:89]
	v_mfma_f32_16x16x32_bf16 v[82:85], v[154:157], v[178:181], v[82:85]
	v_mfma_f32_16x16x32_bf16 v[70:73], v[146:149], v[186:189], v[70:73]
	v_mfma_f32_16x16x32_bf16 v[66:69], v[154:157], v[186:189], v[66:69]
	v_mfma_f32_16x16x32_bf16 v[118:121], v[150:153], v[166:169], v[118:121]
	v_mfma_f32_16x16x32_bf16 v[114:117], v[158:161], v[166:169], v[114:117]
	v_mfma_f32_16x16x32_bf16 v[102:105], v[150:153], v[174:177], v[102:105]
	v_mfma_f32_16x16x32_bf16 v[98:101], v[158:161], v[174:177], v[98:101]
	v_mfma_f32_16x16x32_bf16 v[86:89], v[150:153], v[182:185], v[86:89]
	v_mfma_f32_16x16x32_bf16 v[82:85], v[158:161], v[182:185], v[82:85]
	v_mfma_f32_16x16x32_bf16 v[70:73], v[150:153], v[190:193], v[70:73]
	v_mfma_f32_16x16x32_bf16 v[66:69], v[158:161], v[190:193], v[66:69]
	s_setprio 0
	s_barrier
	s_add_i32 s22, s62, s26
	v_lshl_add_u64 v[216:217], s[44:45], 0, v[0:1]
	s_mov_b32 m0, s22
	ds_read_b128 v[162:165], v244 offset:16384
	ds_read_b128 v[166:169], v244 offset:17408
	ds_read_b128 v[170:173], v244 offset:18432
	ds_read_b128 v[174:177], v244 offset:19456
	ds_read_b128 v[178:181], v244 offset:20480
	ds_read_b128 v[182:185], v244 offset:21504
	ds_read_b128 v[186:189], v244 offset:22528
	ds_read_b128 v[190:193], v244 offset:23552
	global_load_lds_dwordx4 v[216:217], off
	s_add_i32 m0, s22, 0x2000
	s_add_u32 s22, s44, 0x40000
	v_lshl_add_u64 v[218:219], s[44:45], 0, v[210:211]
	s_addc_u32 s23, s45, 0
	s_add_i32 s62, s63, s26
	global_load_lds_dwordx4 v[218:219], off
	v_lshl_add_u64 v[220:221], s[22:23], 0, v[0:1]
	s_mov_b32 m0, s62
	v_lshl_add_u64 v[222:223], s[46:47], 0, v[208:209]
	global_load_lds_dwordx4 v[220:221], off
	v_lshl_add_u64 v[220:221], s[22:23], 0, v[210:211]
	s_add_i32 m0, s62, 0x2000
	s_nop 0
	global_load_lds_dwordx4 v[220:221], off
	v_lshl_add_u64 v[220:221], s[46:47], 0, v[206:207]
	s_mov_b32 m0, s27
	s_nop 0
	global_load_lds_dwordx4 v[220:221], off
	s_mov_b32 m0, s28
	s_nop 0
	global_load_lds_dwordx4 v[222:223], off
	s_waitcnt vmcnt(8)
	s_waitcnt lgkmcnt(0)
	s_barrier
; #define PG8_STAGE(bufoff, gbase, voff) do { _Pragma("unroll") for (int _i = 0; _i < 2; ++_i) \
;         __builtin_amdgcn_global_load_lds((const unsigned*)((const char*)(gbase) + (voff)[_i]), (LAS unsigned*)(lds + (bufoff) + ldsw + _i * 8192), 16, 0, 0); } while (0)
; #define PG8_LDA(dst, b, h) do { _Pragma("unroll") for (int m = 0; m < 4; ++m) _Pragma("unroll") for (int k = 0; k < 2; ++k) dst[m][k] = *(const LAS bf16x8*)(lds + PG8_SA(b, h) + aoff + m * 2048 + k * 1024); } while (0)
; #define PG8_LDB(dst, b, h) do { _Pragma("unroll") for (int n = 0; n < 2; ++n) _Pragma("unroll") for (int k = 0; k < 2; ++k) dst[n][k] = *(const LAS bf16x8*)(lds + PG8_SB(b, h) + boff + n * 2048 + k * 1024); } while (0)
; #define PG8_MMA(ai, bj, At, Bt) do { __builtin_amdgcn_s_setprio(1); _Pragma("unroll") for (int m = 0; m < 4; ++m) _Pragma("unroll") for (int n = 0; n < 2; ++n) _Pragma("unroll") for (int k = 0; k < 2; ++k) \
;         acc[ai][bj][m][n] = __builtin_amdgcn_mfma_f32_16x16x32_bf16(Bt[n][k], At[m][k], acc[ai][bj][m][n], 0, 0, 0); __builtin_amdgcn_s_setprio(0); } while (0)
; #define PG8_WAIT_V(n) asm volatile("s_waitcnt vmcnt(" #n ")" ::: "memory")
; #define PG8_WAIT_L(n) asm volatile("s_waitcnt lgkmcnt(" #n ")" ::: "memory")
; #define PG8_BAR __builtin_amdgcn_s_barrier()
; #define PG8_SCHED __builtin_amdgcn_sched_barrier(0)
; template <class Epi, class Sched>
; __device__ __forceinline__ void gemm_phase(LAS unsigned char* lds, const int lda, const int ldb, const Sched& S, const Epi& E) {
;     ...
;             PG8_WAIT_V(8); PG8_WAIT_L(0); PG8_BAR; PG8_MMA(1, 0, At, B0); PG8_MMA(1, 1, At, B1); PG8_BAR; PG8_SCHED;
;             PG8_LDB(B0, 1, 0); PG8_LDB(B1, 1, 1); PG8_SCHED; PG8_LDA(At, 1, 0); PG8_STAGE(PG8_SA(0, 1), a2 + hstepA, voffA);
;             PG8_WAIT_V(8); PG8_WAIT_L(0); PG8_BAR; PG8_MMA(0, 0, At, B0); PG8_MMA(0, 1, At, B1); PG8_BAR; PG8_SCHED;
	s_setprio 1
	s_waitcnt lgkmcnt(0)
	v_mfma_f32_16x16x32_bf16 v[62:65], v[130:133], v[162:165], v[62:65]
	v_mfma_f32_16x16x32_bf16 v[58:61], v[138:141], v[162:165], v[58:61]
	v_mfma_f32_16x16x32_bf16 v[46:49], v[130:133], v[170:173], v[46:49]
	v_mfma_f32_16x16x32_bf16 v[42:45], v[138:141], v[170:173], v[42:45]
	v_mfma_f32_16x16x32_bf16 v[30:33], v[130:133], v[178:181], v[30:33]
	v_mfma_f32_16x16x32_bf16 v[26:29], v[138:141], v[178:181], v[26:29]
	v_mfma_f32_16x16x32_bf16 v[14:17], v[130:133], v[186:189], v[14:17]
	v_mfma_f32_16x16x32_bf16 v[10:13], v[138:141], v[186:189], v[10:13]
	v_mfma_f32_16x16x32_bf16 v[62:65], v[134:137], v[166:169], v[62:65]
	v_mfma_f32_16x16x32_bf16 v[58:61], v[142:145], v[166:169], v[58:61]
	v_mfma_f32_16x16x32_bf16 v[46:49], v[134:137], v[174:177], v[46:49]
	v_mfma_f32_16x16x32_bf16 v[42:45], v[142:145], v[174:177], v[42:45]
	v_mfma_f32_16x16x32_bf16 v[30:33], v[134:137], v[182:185], v[30:33]
	v_mfma_f32_16x16x32_bf16 v[26:29], v[142:145], v[182:185], v[26:29]
	v_mfma_f32_16x16x32_bf16 v[14:17], v[134:137], v[190:193], v[14:17]
	v_mfma_f32_16x16x32_bf16 v[10:13], v[142:145], v[190:193], v[10:13]
	s_setprio 0
	s_setprio 1
	v_mfma_f32_16x16x32_bf16 v[54:57], v[146:149], v[162:165], v[54:57]
	v_mfma_f32_16x16x32_bf16 v[50:53], v[154:157], v[162:165], v[50:53]
	v_mfma_f32_16x16x32_bf16 v[38:41], v[146:149], v[170:173], v[38:41]
	v_mfma_f32_16x16x32_bf16 v[34:37], v[154:157], v[170:173], v[34:37]
	v_mfma_f32_16x16x32_bf16 v[22:25], v[146:149], v[178:181], v[22:25]
	v_mfma_f32_16x16x32_bf16 v[18:21], v[154:157], v[178:181], v[18:21]
	v_mfma_f32_16x16x32_bf16 v[6:9], v[146:149], v[186:189], v[6:9]
	v_mfma_f32_16x16x32_bf16 v[2:5], v[154:157], v[186:189], v[2:5]
	v_mfma_f32_16x16x32_bf16 v[54:57], v[150:153], v[166:169], v[54:57]
	v_mfma_f32_16x16x32_bf16 v[50:53], v[158:161], v[166:169], v[50:53]
	v_mfma_f32_16x16x32_bf16 v[38:41], v[150:153], v[174:177], v[38:41]
	v_mfma_f32_16x16x32_bf16 v[34:37], v[158:161], v[174:177], v[34:37]
	v_mfma_f32_16x16x32_bf16 v[22:25], v[150:153], v[182:185], v[22:25]
	v_mfma_f32_16x16x32_bf16 v[18:21], v[158:161], v[182:185], v[18:21]
	v_mfma_f32_16x16x32_bf16 v[6:9], v[150:153], v[190:193], v[6:9]
	v_mfma_f32_16x16x32_bf16 v[2:5], v[158:161], v[190:193], v[2:5]
	s_setprio 0
	s_barrier
	s_add_i32 s62, 0, 0x18000
	s_add_i32 s63, 0, 0x1c000
	v_add_u32_e32 v142, s62, v241
	v_add_u32_e32 v158, s63, v241
	ds_read_b128 v[130:133], v142
	ds_read_b128 v[134:137], v142 offset:1024
	ds_read_b128 v[138:141], v142 offset:2048
	ds_read_b128 v[142:145], v142 offset:3072
	ds_read_b128 v[146:149], v158
	ds_read_b128 v[150:153], v158 offset:1024
	ds_read_b128 v[154:157], v158 offset:2048
	ds_read_b128 v[158:161], v158 offset:3072
	s_add_u32 s22, s46, 0x190000
	s_addc_u32 s23, s47, 0
	s_mov_b32 m0, s29
	v_lshl_add_u64 v[224:225], s[22:23], 0, v[206:207]
	ds_read_b128 v[162:165], v244 offset:32768
	ds_read_b128 v[166:169], v244 offset:33792
	ds_read_b128 v[170:173], v244 offset:34816
	ds_read_b128 v[174:177], v244 offset:35840
	ds_read_b128 v[178:181], v244 offset:36864
	ds_read_b128 v[182:185], v244 offset:37888
	ds_read_b128 v[186:189], v244 offset:38912
	ds_read_b128 v[190:193], v244 offset:39936
	global_load_lds_dwordx4 v[224:225], off
	v_lshl_add_u64 v[224:225], s[22:23], 0, v[208:209]
	s_mov_b32 m0, s33
	s_nop 0
	global_load_lds_dwordx4 v[224:225], off
	s_waitcnt vmcnt(8)
	s_waitcnt lgkmcnt(0)
	s_barrier
	s_setprio 1
	s_waitcnt lgkmcnt(0)
	v_mfma_f32_16x16x32_bf16 v[126:129], v[130:133], v[162:165], v[126:129]
	v_mfma_f32_16x16x32_bf16 v[122:125], v[138:141], v[162:165], v[122:125]
	v_mfma_f32_16x16x32_bf16 v[110:113], v[130:133], v[170:173], v[110:113]
	v_mfma_f32_16x16x32_bf16 v[106:109], v[138:141], v[170:173], v[106:109]
	v_mfma_f32_16x16x32_bf16 v[94:97], v[130:133], v[178:181], v[94:97]
	v_mfma_f32_16x16x32_bf16 v[90:93], v[138:141], v[178:181], v[90:93]
	v_mfma_f32_16x16x32_bf16 v[78:81], v[130:133], v[186:189], v[78:81]
	v_mfma_f32_16x16x32_bf16 v[74:77], v[138:141], v[186:189], v[74:77]
	v_mfma_f32_16x16x32_bf16 v[126:129], v[134:137], v[166:169], v[126:129]
	v_mfma_f32_16x16x32_bf16 v[122:125], v[142:145], v[166:169], v[122:125]
	v_mfma_f32_16x16x32_bf16 v[110:113], v[134:137], v[174:177], v[110:113]
	v_mfma_f32_16x16x32_bf16 v[106:109], v[142:145], v[174:177], v[106:109]
	v_mfma_f32_16x16x32_bf16 v[94:97], v[134:137], v[182:185], v[94:97]
	v_mfma_f32_16x16x32_bf16 v[90:93], v[142:145], v[182:185], v[90:93]
	v_mfma_f32_16x16x32_bf16 v[78:81], v[134:137], v[190:193], v[78:81]
	v_mfma_f32_16x16x32_bf16 v[74:77], v[142:145], v[190:193], v[74:77]
	s_setprio 0
	s_setprio 1
	v_mfma_f32_16x16x32_bf16 v[118:121], v[146:149], v[162:165], v[118:121]
	v_mfma_f32_16x16x32_bf16 v[114:117], v[154:157], v[162:165], v[114:117]
	v_mfma_f32_16x16x32_bf16 v[102:105], v[146:149], v[170:173], v[102:105]
	v_mfma_f32_16x16x32_bf16 v[98:101], v[154:157], v[170:173], v[98:101]
	v_mfma_f32_16x16x32_bf16 v[86:89], v[146:149], v[178:181], v[86:89]
	v_mfma_f32_16x16x32_bf16 v[82:85], v[154:157], v[178:181], v[82:85]
	v_mfma_f32_16x16x32_bf16 v[70:73], v[146:149], v[186:189], v[70:73]
	v_mfma_f32_16x16x32_bf16 v[66:69], v[154:157], v[186:189], v[66:69]
	v_mfma_f32_16x16x32_bf16 v[118:121], v[150:153], v[166:169], v[118:121]
	v_mfma_f32_16x16x32_bf16 v[114:117], v[158:161], v[166:169], v[114:117]
	v_mfma_f32_16x16x32_bf16 v[102:105], v[150:153], v[174:177], v[102:105]
	v_mfma_f32_16x16x32_bf16 v[98:101], v[158:161], v[174:177], v[98:101]
	v_mfma_f32_16x16x32_bf16 v[86:89], v[150:153], v[182:185], v[86:89]
	v_mfma_f32_16x16x32_bf16 v[82:85], v[158:161], v[182:185], v[82:85]
	v_mfma_f32_16x16x32_bf16 v[70:73], v[150:153], v[190:193], v[70:73]
	v_mfma_f32_16x16x32_bf16 v[66:69], v[158:161], v[190:193], v[66:69]
	s_setprio 0
	s_barrier
; #define PG8_STAGE(bufoff, gbase, voff) do { _Pragma("unroll") for (int _i = 0; _i < 2; ++_i) \
;         __builtin_amdgcn_global_load_lds((const unsigned*)((const char*)(gbase) + (voff)[_i]), (LAS unsigned*)(lds + (bufoff) + ldsw + _i * 8192), 16, 0, 0); } while (0)
; #define PG8_LDA(dst, b, h) do { _Pragma("unroll") for (int m = 0; m < 4; ++m) _Pragma("unroll") for (int k = 0; k < 2; ++k) dst[m][k] = *(const LAS bf16x8*)(lds + PG8_SA(b, h) + aoff + m * 2048 + k * 1024); } while (0)
; #define PG8_MMA(ai, bj, At, Bt) do { __builtin_amdgcn_s_setprio(1); _Pragma("unroll") for (int m = 0; m < 4; ++m) _Pragma("unroll") for (int n = 0; n < 2; ++n) _Pragma("unroll") for (int k = 0; k < 2; ++k) \
;         acc[ai][bj][m][n] = __builtin_amdgcn_mfma_f32_16x16x32_bf16(Bt[n][k], At[m][k], acc[ai][bj][m][n], 0, 0, 0); __builtin_amdgcn_s_setprio(0); } while (0)
; #define PG8_WAIT_V(n) asm volatile("s_waitcnt vmcnt(" #n ")" ::: "memory")
; #define PG8_WAIT_L(n) asm volatile("s_waitcnt lgkmcnt(" #n ")" ::: "memory")
; #define PG8_BAR __builtin_amdgcn_s_barrier()
; #define PG8_SCHED __builtin_amdgcn_sched_barrier(0)
; template <class Epi, class Sched>
; __device__ __forceinline__ void gemm_phase(LAS unsigned char* lds, const int lda, const int ldb, const Sched& S, const Epi& E) {
;     ...
;             PG8_LDA(At, 1, 1); PG8_STAGE(PG8_SB(1, 0), b3, voffB); PG8_STAGE(PG8_SB(1, 1), b3 + hstepB, voffB); PG8_STAGE(PG8_SA(1, 0), a3, voffA);
;             PG8_WAIT_V(8); PG8_WAIT_L(0); PG8_BAR; PG8_MMA(1, 0, At, B0); PG8_MMA(1, 1, At, B1); PG8_BAR; PG8_SCHED;
;         }
;         if (wr == 0) PG8_BAR;
;     DI void operator()(f32x4 (&acc)[2][2][4][2], const pg8::GUnit& u, int wr, int wc, int fr, int fq) const {
;     ...
;             for (int ai = 0; ai < 2; ++ai) {
;                 u32x4 gq[4][2], mq[4][2];
; #pragma unroll
;                 for (int m = 0; m < 4; ++m) { const bf16_t* rp = act + (size_t)(row0 + ai * 128 + m * 16) * PITCH + col0;
; #pragma unroll
;                     for (int bj = 0; bj < 2; ++bj) { gq[m][bj] = *(const u32x4*)(rp + C_GS + bj * 128); if (z > 1) mq[m][bj] = *(const u32x4*)(rp + C_MERGED + bj * 128); } }
	s_add_i32 s22, s62, s26
	v_lshl_add_u64 v[216:217], v[216:217], 0, s[82:83]
	s_mov_b32 m0, s22
	ds_read_b128 v[162:165], v244 offset:49152
	ds_read_b128 v[166:169], v244 offset:50176
	ds_read_b128 v[170:173], v244 offset:51200
	ds_read_b128 v[174:177], v244 offset:52224
	ds_read_b128 v[178:181], v244 offset:53248
	ds_read_b128 v[182:185], v244 offset:54272
	ds_read_b128 v[186:189], v244 offset:55296
	ds_read_b128 v[190:193], v244 offset:56320
	global_load_lds_dwordx4 v[216:217], off
	s_add_i32 m0, s22, 0x2000
	s_add_u32 s22, s44, 0x40080
	v_lshl_add_u64 v[216:217], v[218:219], 0, s[82:83]
	s_addc_u32 s23, s45, 0
	s_add_i32 s44, s63, s26
	global_load_lds_dwordx4 v[216:217], off
	v_lshl_add_u64 v[216:217], s[22:23], 0, v[0:1]
	s_mov_b32 m0, s44
	s_nop 0
	global_load_lds_dwordx4 v[216:217], off
	v_lshl_add_u64 v[216:217], s[22:23], 0, v[210:211]
	s_add_i32 m0, s44, 0x2000
	s_nop 0
	global_load_lds_dwordx4 v[216:217], off
	v_lshl_add_u64 v[216:217], v[220:221], 0, s[82:83]
	s_mov_b32 m0, s38
	s_nop 0
	global_load_lds_dwordx4 v[216:217], off
	v_lshl_add_u64 v[216:217], v[222:223], 0, s[82:83]
	s_mov_b32 m0, s48
	s_nop 0
	global_load_lds_dwordx4 v[216:217], off
	s_waitcnt vmcnt(8)
	s_waitcnt lgkmcnt(0)
	s_barrier
	s_setprio 1
	s_waitcnt lgkmcnt(0)
	v_mfma_f32_16x16x32_bf16 v[62:65], v[130:133], v[162:165], v[62:65]
	v_mfma_f32_16x16x32_bf16 v[58:61], v[138:141], v[162:165], v[58:61]
	v_mfma_f32_16x16x32_bf16 v[46:49], v[130:133], v[170:173], v[46:49]
	v_mfma_f32_16x16x32_bf16 v[42:45], v[138:141], v[170:173], v[42:45]
	v_mfma_f32_16x16x32_bf16 v[30:33], v[130:133], v[178:181], v[30:33]
	v_mfma_f32_16x16x32_bf16 v[26:29], v[138:141], v[178:181], v[26:29]
	v_mfma_f32_16x16x32_bf16 v[14:17], v[130:133], v[186:189], v[14:17]
	v_mfma_f32_16x16x32_bf16 v[10:13], v[138:141], v[186:189], v[10:13]
	v_mfma_f32_16x16x32_bf16 v[62:65], v[134:137], v[166:169], v[62:65]
	v_mfma_f32_16x16x32_bf16 v[58:61], v[142:145], v[166:169], v[58:61]
	v_mfma_f32_16x16x32_bf16 v[46:49], v[134:137], v[174:177], v[46:49]
	v_mfma_f32_16x16x32_bf16 v[42:45], v[142:145], v[174:177], v[42:45]
	v_mfma_f32_16x16x32_bf16 v[30:33], v[134:137], v[182:185], v[30:33]
	v_mfma_f32_16x16x32_bf16 v[26:29], v[142:145], v[182:185], v[26:29]
	v_mfma_f32_16x16x32_bf16 v[14:17], v[134:137], v[190:193], v[14:17]
	v_mfma_f32_16x16x32_bf16 v[10:13], v[142:145], v[190:193], v[10:13]
	s_setprio 0
	s_setprio 1
	v_mfma_f32_16x16x32_bf16 v[54:57], v[146:149], v[162:165], v[54:57]
	v_mfma_f32_16x16x32_bf16 v[50:53], v[154:157], v[162:165], v[50:53]
	v_mfma_f32_16x16x32_bf16 v[38:41], v[146:149], v[170:173], v[38:41]
	v_mfma_f32_16x16x32_bf16 v[34:37], v[154:157], v[170:173], v[34:37]
	v_mfma_f32_16x16x32_bf16 v[22:25], v[146:149], v[178:181], v[22:25]
	v_mfma_f32_16x16x32_bf16 v[18:21], v[154:157], v[178:181], v[18:21]
	v_mfma_f32_16x16x32_bf16 v[6:9], v[146:149], v[186:189], v[6:9]
	v_mfma_f32_16x16x32_bf16 v[2:5], v[154:157], v[186:189], v[2:5]
	v_mfma_f32_16x16x32_bf16 v[54:57], v[150:153], v[166:169], v[54:57]
	v_mfma_f32_16x16x32_bf16 v[50:53], v[158:161], v[166:169], v[50:53]
	v_mfma_f32_16x16x32_bf16 v[38:41], v[150:153], v[174:177], v[38:41]
	v_mfma_f32_16x16x32_bf16 v[34:37], v[158:161], v[174:177], v[34:37]
	v_mfma_f32_16x16x32_bf16 v[22:25], v[150:153], v[182:185], v[22:25]
	v_mfma_f32_16x16x32_bf16 v[18:21], v[158:161], v[182:185], v[18:21]
	v_mfma_f32_16x16x32_bf16 v[6:9], v[150:153], v[190:193], v[6:9]
	v_mfma_f32_16x16x32_bf16 v[2:5], v[158:161], v[190:193], v[2:5]
	s_setprio 0
	s_cmp_ge_i32 s61, s59
	s_cbranch_scc0 .Lmo_pre_skip
	s_bitcmp0_b32 s58, 0
	s_cbranch_scc1 .Lmo_pre_skip
	v_lshl_add_u32 v245, s57, 8, v240
	v_lshl_or_b32 v216, s56, 8, v243
	v_ashrrev_i32_e32 v217, 31, v216
	v_lshl_add_u64 v[218:219], v[216:217], 1, s[6:7]
	v_mad_i64_i32 v[252:253], s[100:101], v245, s31, v[218:219]
	s_lshl_b32 s98, s31, 4
	s_mov_b32 s99, 0
	s_movk_i32 s100, 0x1000
	s_mov_b32 s101, 0
	v_mov_b32_e32 v254, v252
	v_mov_b32_e32 v255, v253
	s_cmp_gt_i32 s58, 1
	s_cbranch_scc0 .Lmo_ld1_nm
	v_lshl_add_u64 v[186:187], v[254:255], 0, s[100:101]
	global_load_dwordx4 v[190:193], v[186:187], off offset:1024
	global_load_dwordx4 v[186:189], v[186:187], off offset:1280
	global_load_dwordx4 v[158:161], v[254:255], off offset:1024
	global_load_dwordx4 v[154:157], v[254:255], off offset:1280
	v_lshl_add_u64 v[254:255], v[254:255], 0, s[98:99]
	v_lshl_add_u64 v[178:179], v[254:255], 0, s[100:101]
	global_load_dwordx4 v[182:185], v[178:179], off offset:1024
	global_load_dwordx4 v[178:181], v[178:179], off offset:1280
	global_load_dwordx4 v[150:153], v[254:255], off offset:1024
	global_load_dwordx4 v[146:149], v[254:255], off offset:1280
	v_lshl_add_u64 v[254:255], v[254:255], 0, s[98:99]
	v_lshl_add_u64 v[170:171], v[254:255], 0, s[100:101]
	global_load_dwordx4 v[174:177], v[170:171], off offset:1024
	global_load_dwordx4 v[170:173], v[170:171], off offset:1280
	global_load_dwordx4 v[142:145], v[254:255], off offset:1024
	global_load_dwordx4 v[138:141], v[254:255], off offset:1280
	v_lshl_add_u64 v[254:255], v[254:255], 0, s[98:99]
	v_lshl_add_u64 v[162:163], v[254:255], 0, s[100:101]
	global_load_dwordx4 v[166:169], v[162:163], off offset:1024
	global_load_dwordx4 v[162:165], v[162:163], off offset:1280
	global_load_dwordx4 v[134:137], v[254:255], off offset:1024
	global_load_dwordx4 v[130:133], v[254:255], off offset:1280
	s_branch .Lmo_pre_skip

; DI unsigned cvtpk(float lo, float hi) { typedef float f2 __attribute__((ext_vector_type(2))); typedef __bf16 b2 __attribute__((ext_vector_type(2))); f2 v = {lo, hi}; b2 b = __builtin_convertvector(v, b2); return __builtin_bit_cast(unsigned, b); }
; DI float bflo(unsigned w) { return __uint_as_float(w << 16); }
; DI float bfhi(unsigned w) { return __uint_as_float(w & 0xffff0000u); }
; #define PG8_BAR __builtin_amdgcn_s_barrier()
; template <class Epi, class Sched>
; __device__ __forceinline__ void gemm_phase(LAS unsigned char* lds, const int lda, const int ldb, const Sched& S, const Epi& E) {
;     ...
;         if (wr == 0) PG8_BAR;
;         E(acc, cur, wr, wc, fr, fq);
;         if (!has_next) break;
;     DI void operator()(f32x4 (&acc)[2][2][4][2], const pg8::GUnit& u, int wr, int wc, int fr, int fq) const {
;     ...
;                 for (int m = 0; m < 4; ++m) { bf16_t* mp = act + (size_t)(row0 + ai * 128 + m * 16) * PITCH + C_MERGED + col0;
; #pragma unroll
;                     for (int bj = 0; bj < 2; ++bj) {
;                         const u32x4 g = gq[m][bj];
;                         const f32x4 a0 = acc[ai][bj][m][0], a1 = acc[ai][bj][m][1];
;                         float r0 = bflo(g.x) * a0[0], r1 = bfhi(g.x) * a0[1], r2 = bflo(g.y) * a0[2], r3 = bfhi(g.y) * a0[3];
;                         float r4 = bflo(g.z) * a1[0], r5 = bfhi(g.z) * a1[1], r6 = bflo(g.w) * a1[2], r7 = bfhi(g.w) * a1[3];
;                         if (z > 1) { const u32x4 pm_ = mq[m][bj];
;                             r0 += bflo(pm_.x); r1 += bfhi(pm_.x); r2 += bflo(pm_.y); r3 += bfhi(pm_.y); r4 += bflo(pm_.z); r5 += bfhi(pm_.z); r6 += bflo(pm_.w); r7 += bfhi(pm_.w); }
;                         u32x4 w; w.x = cvtpk(r0, r1); w.y = cvtpk(r2, r3); w.z = cvtpk(r4, r5); w.w = cvtpk(r6, r7);
;                         *(u32x4*)(mp + bj * 128) = w;
;                     } }
.Lmo_pre_skip:
	s_barrier
	s_add_u32 s25, s25, 0x100
	s_addc_u32 s60, s60, 0
	s_cmp_ge_i32 s61, s59
	s_mov_b64 s[22:23], s[36:37]
	s_mov_b32 s44, s61
	s_cbranch_scc0 .LBB0_662
	s_and_b64 vcc, exec, s[14:15]
	s_cbranch_vccz .LBB0_665
	s_barrier
.LBB0_665:
	v_lshl_add_u32 v245, s57, 8, v240
	v_lshl_or_b32 v216, s56, 8, v243
	s_bitcmp0_b32 s58, 0
	s_mov_b64 s[22:23], -1
	s_cbranch_scc1 .LBB0_731
	s_cmp_gt_i32 s58, 1
	s_cselect_b64 s[44:45], 0, -1
	s_lshl_b32 s100, s31, 7
	s_add_u32 s22, s100, 0x1000
	s_mov_b32 s23, 0
	s_waitcnt vmcnt(0)
	s_and_b64 vcc, exec, s[44:45]
	s_cbranch_vccnz .Lmo_h1nm_0
	v_lshlrev_b32_e32 v218, 16, v190
	v_and_b32_e32 v219, 0xffff0000, v190
	v_lshlrev_b32_e32 v220, 16, v191
	v_and_b32_e32 v221, 0xffff0000, v191
	v_lshlrev_b32_e32 v222, 16, v192
	v_and_b32_e32 v223, 0xffff0000, v192
	v_lshlrev_b32_e32 v224, 16, v193
	v_and_b32_e32 v225, 0xffff0000, v193
	v_pk_mul_f32 v[218:219], v[126:127], v[218:219]
	v_pk_mul_f32 v[220:221], v[128:129], v[220:221]
	v_pk_mul_f32 v[222:223], v[122:123], v[222:223]
	v_pk_mul_f32 v[224:225], v[124:125], v[224:225]
	v_lshlrev_b32_e32 v190, 16, v158
	v_and_b32_e32 v191, 0xffff0000, v158
	v_pk_add_f32 v[218:219], v[218:219], v[190:191]
	v_lshlrev_b32_e32 v192, 16, v159
	v_and_b32_e32 v193, 0xffff0000, v159
	v_pk_add_f32 v[220:221], v[220:221], v[192:193]
	v_lshlrev_b32_e32 v190, 16, v160
	v_and_b32_e32 v191, 0xffff0000, v160
	v_pk_add_f32 v[222:223], v[222:223], v[190:191]
	v_lshlrev_b32_e32 v192, 16, v161
	v_and_b32_e32 v193, 0xffff0000, v161
	v_pk_add_f32 v[224:225], v[224:225], v[192:193]
	v_cvt_pk_bf16_f32 v218, v218, v219
	v_cvt_pk_bf16_f32 v219, v220, v221
	v_cvt_pk_bf16_f32 v220, v222, v223
	v_cvt_pk_bf16_f32 v221, v224, v225
	global_store_dwordx4 v[252:253], v[218:221], off offset:1024
	v_lshl_add_u64 v[190:191], v[252:253], 0, s[22:23]
	v_lshl_add_u64 v[158:159], v[252:253], 0, s[100:101]
	global_load_dwordx4 v[190:193], v[190:191], off offset:1024
	global_load_dwordx4 v[158:161], v[158:159], off offset:1024
	s_branch .Lmo_h1e_0
